# RWKV first-segment blocks skip the segment-2-only accumulator copy web at the S1 merge
# speedup vs baseline: 1.0800x; 1.0011x over previous
.LBB0_426:
	s_cmp_lg_u64 s[40:41], 0
	s_cbranch_scc1 .Lrw_mrg_full
	v_cndmask_b32_e64 v8, 0, 1, s[48:49]
	s_and_b64 vcc, exec, s[12:13]
	v_cmp_ne_u32_e64 s[8:9], 1, v8
	s_branch .Lrw_mrg_done

.Lrw_mrg_done:
	s_cbranch_vccz .LBB0_434
	s_cmp_lg_u64 s[40:41], 0
	s_cbranch_scc1 .Lrz_skip1
	v_and_b32_e32 v20, 15, v161
	s_add_i32 s98, s0, s42
	v_add_u32_e32 v20, s98, v20
	v_subrev_u32_e32 v20, 63, v20
	v_mul_lo_u32 v20, v20, s64
	v_lshrrev_b32_e32 v21, 4, v161
	v_lshl_add_u32 v20, v21, 3, v20
	v_add_u32_e32 v20, s92, v20
	v_add_u32_e32 v20, 0x1e00, v20
	v_readlane_b32 s98, v252, 29
	v_readlane_b32 s99, v252, 30
	s_nop 4
	global_load_dwordx2 v[184:185], v20, s[98:99]
	global_load_dwordx2 v[186:187], v20, s[98:99] offset:32
	global_load_dwordx2 v[188:189], v20, s[98:99] offset:64
	global_load_dwordx2 v[224:225], v20, s[98:99] offset:96
